# w_out and ffn_out tail epilogues: residual, previous-LN statistics and gamma/beta loads all requested before the cross-wave LDS reduction instead of three serial load-wait stages
# speedup vs baseline: 1.0025x; 1.0025x over previous
; #define LAS __attribute__((address_space(3)))
; __device__ __forceinline__ float bflo(unsigned w) { return __uint_as_float(w << 16); }
; __device__ __forceinline__ float bfhi(unsigned w) { return __uint_as_float(w & 0xffff0000u); }
; __device__ __forceinline__ u32x4 pack8(f32x4 a, f32x4 b) { u32x4 w; w.x = cvtpk(a[0], a[1]); w.y = cvtpk(a[2], a[3]); w.z = cvtpk(b[0], b[1]); w.w = cvtpk(b[2], b[3]); return w; }
; #define BAR_LDS() do { asm volatile("s_waitcnt lgkmcnt(0)" ::: "memory"); __builtin_amdgcn_s_barrier(); asm volatile("" ::: "memory"); } while (0)
; template <int EPI> __device__ __forceinline__ void tail_gemm(LAS unsigned char* lds, const bf16* Am, const bf16* Bt, int K, const TailEpi& E, int tid_in) {
;     ...
;     LAS float* part = (LAS float*)lds + (size_t)w * 64 * 65;
; #pragma unroll
;     for (int i = 0; i < 4; ++i)
; #pragma unroll
;         for (int j = 0; j < 4; ++j)
; #pragma unroll
;             for (int r = 0; r < 4; ++r) part[(16 * i + 4 * q4 + r) * 65 + 16 * j + l15] = acc[i][j][r];
;     BAR_LDS();
;     ...
;     const size_t off = (size_t)row * 1024 + col;
;     if (EPI == 0 || EPI == 1) {
;         const u32x4 s = *(const u32x4*)(E.S + off);
;         v0[0] *= bflo(s.x); v0[1] *= bfhi(s.x); v0[2] *= bflo(s.y); v0[3] *= bfhi(s.y); v1[0] *= bflo(s.z); v1[1] *= bfhi(s.z); v1[2] *= bflo(s.w); v1[3] *= bfhi(s.w);
;         if (EPI == 1) { const u32x4 a = *(const u32x4*)(E.A + off);
;             v0[0] += bflo(a.x); v0[1] += bfhi(a.x); v0[2] += bflo(a.y); v0[3] += bfhi(a.y); v1[0] += bflo(a.z); v1[1] += bfhi(a.z); v1[2] += bflo(a.w); v1[3] += bfhi(a.w); }
;         *(u32x4*)(E.S + off) = pack8(v0, v1);
;     } else {
;         const u32x4 zw = *(const u32x4*)(E.ZB + off);
;         f32x4 x0 = {bflo(zw.x), bfhi(zw.x), bflo(zw.y), bfhi(zw.y)}, x1 = {bflo(zw.z), bfhi(zw.z), bflo(zw.w), bfhi(zw.w)};
;         if (E.pst) {
;             const f32x4* sp = (const f32x4*)(E.pst + (size_t)row * 32); float s = 0.f, q = 0.f;
; #pragma unroll
;             for (int i = 0; i < 8; ++i) { const f32x4 t = sp[i]; s += t[0] + t[2]; q += t[1] + t[3]; }
;             const float mu = s * (1.f / D), rstd = __builtin_amdgcn_rsqf(fmaxf(q * (1.f / D) - mu * mu, 0.f) + LN_EPS);
;             const f32x4 g0 = *(const f32x4*)(E.pg + col), g1 = *(const f32x4*)(E.pg + col + 4), b0 = *(const f32x4*)(E.pb + col), b1 = *(const f32x4*)(E.pb + col + 4);
.LBB0_1528:
	s_or_b64 exec, exec, s[4:5]
	ds_write2_b32 v181, v60, v56 offset1:16
	ds_write2_b32 v181, v61, v57 offset0:65 offset1:81
	ds_write2_b32 v181, v62, v58 offset0:130 offset1:146
	ds_write2_b32 v181, v63, v59 offset0:195 offset1:211
	ds_write2_b32 v181, v44, v40 offset0:32 offset1:48
	ds_write2_b32 v181, v45, v41 offset0:97 offset1:113
	ds_write2_b32 v181, v46, v42 offset0:162 offset1:178
	ds_write2_b32 v181, v47, v43 offset0:227 offset1:243
	v_add_u32_e32 v40, 0x1000, v181
	ds_write2_b32 v40, v28, v24 offset0:16 offset1:32
	ds_write2_b32 v40, v29, v25 offset0:81 offset1:97
	ds_write2_b32 v40, v30, v26 offset0:146 offset1:162
	ds_write2_b32 v40, v31, v27 offset0:211 offset1:227
	ds_write2_b32 v40, v12, v8 offset0:48 offset1:64
	ds_write2_b32 v40, v13, v9 offset0:113 offset1:129
	ds_write2_b32 v40, v14, v10 offset0:178 offset1:194
	v_add_u32_e32 v8, 0x1200, v181
	ds_write2_b32 v8, v15, v11 offset0:115 offset1:131
	v_add_u32_e32 v8, 0x2000, v181
	ds_write2_b32 v8, v48, v52 offset0:32 offset1:48
	ds_write2_b32 v8, v49, v53 offset0:97 offset1:113
	ds_write2_b32 v8, v50, v54 offset0:162 offset1:178
	ds_write2_b32 v8, v51, v55 offset0:227 offset1:243
	ds_write2_b32 v8, v32, v36 offset0:64 offset1:80
	ds_write2_b32 v8, v33, v37 offset0:129 offset1:145
	ds_write2_b32 v8, v34, v38 offset0:194 offset1:210
	v_add_u32_e32 v8, 0x2400, v181
	ds_write2_b32 v8, v35, v39 offset0:3 offset1:19
	v_add_u32_e32 v8, 0x3000, v181
	v_add_u32_e32 v9, 0x3200, v181
	ds_write2_b32 v8, v16, v20 offset0:48 offset1:64
	ds_write2_b32 v8, v17, v21 offset0:113 offset1:129
	ds_write2_b32 v8, v18, v22 offset0:178 offset1:194
	ds_write2_b32 v9, v19, v23 offset0:115 offset1:131
	ds_write2_b32 v8, v0, v4 offset0:80 offset1:96
	ds_write2_b32 v8, v1, v5 offset0:145 offset1:161
	ds_write2_b32 v8, v2, v6 offset0:210 offset1:226
	v_add_u32_e32 v0, 0x3400, v181
	v_add_u32_e32 v2, s1, v178
	ds_write2_b32 v0, v3, v7 offset0:19 offset1:35
	v_ashrrev_i32_e32 v3, 31, v2
	s_waitcnt vmcnt(5)
	v_add_u32_e32 v172, s1, v178
	v_ashrrev_i32_e32 v173, 31, v172
	v_or_b32_e32 v114, s0, v179
	v_lshlrev_b64 v[174:175], 11, v[172:173]
	v_lshl_add_u64 v[174:175], s[20:21], 0, v[174:175]
	v_lshlrev_b32_e32 v80, 1, v114
	v_lshl_add_u64 v[174:175], v[174:175], 0, v[80:81]
	global_load_dwordx4 v[116:119], v[174:175], off
	s_and_b64 vcc, exec, s[2:3]
	s_cbranch_vccz .Lte5_nostats
	v_lshlrev_b64 v[172:173], 7, v[172:173]
	v_lshl_add_u64 v[172:173], s[46:47], 0, v[172:173]
	v_lshlrev_b32_e32 v114, 2, v114
	global_load_dwordx4 v[120:123], v[172:173], off offset:48
	global_load_dwordx4 v[124:127], v[172:173], off offset:32
	global_load_dwordx4 v[128:131], v[172:173], off offset:16
	global_load_dwordx4 v[132:135], v[172:173], off
	global_load_dwordx4 v[136:139], v[172:173], off offset:112
	global_load_dwordx4 v[140:143], v[172:173], off offset:96
	global_load_dwordx4 v[144:147], v[172:173], off offset:80
	global_load_dwordx4 v[148:151], v[172:173], off offset:64
	global_load_dwordx4 v[152:155], v114, s[48:49] offset:16
	global_load_dwordx4 v[156:159], v114, s[48:49]
	global_load_dwordx4 v[160:163], v114, s[50:51] offset:16
	global_load_dwordx4 v[168:171], v114, s[50:51]
; #define LAS __attribute__((address_space(3)))
; __device__ __forceinline__ float bflo(unsigned w) { return __uint_as_float(w << 16); }
; __device__ __forceinline__ float bfhi(unsigned w) { return __uint_as_float(w & 0xffff0000u); }
; __device__ __forceinline__ u32x4 pack8(f32x4 a, f32x4 b) { u32x4 w; w.x = cvtpk(a[0], a[1]); w.y = cvtpk(a[2], a[3]); w.z = cvtpk(b[0], b[1]); w.w = cvtpk(b[2], b[3]); return w; }
; template <int EPI> __device__ __forceinline__ void tail_gemm(LAS unsigned char* lds, const bf16* Am, const bf16* Bt, int K, const TailEpi& E, int tid_in) {
;     ...
;     const int rl = tid >> 3, c8 = (tid & 7) * 8, row = row0 + rl, col = col0 + c8;
;     f32x4 v0 = {0.f, 0.f, 0.f, 0.f}, v1 = v0;
; #pragma unroll
;     for (int ww = 0; ww < 8; ++ww) { const LAS float* p = (const LAS float*)lds + (size_t)ww * 64 * 65 + rl * 65 + c8;
;         v0[0] += p[0]; v0[1] += p[1]; v0[2] += p[2]; v0[3] += p[3]; v1[0] += p[4]; v1[1] += p[5]; v1[2] += p[6]; v1[3] += p[7]; }
;     const size_t off = (size_t)row * 1024 + col;
;     if (EPI == 0 || EPI == 1) {
;         const u32x4 s = *(const u32x4*)(E.S + off);
;         v0[0] *= bflo(s.x); v0[1] *= bfhi(s.x); v0[2] *= bflo(s.y); v0[3] *= bfhi(s.y); v1[0] *= bflo(s.z); v1[1] *= bfhi(s.z); v1[2] *= bflo(s.w); v1[3] *= bfhi(s.w);
;         if (EPI == 1) { const u32x4 a = *(const u32x4*)(E.A + off);
;             v0[0] += bflo(a.x); v0[1] += bfhi(a.x); v0[2] += bflo(a.y); v0[3] += bfhi(a.y); v1[0] += bflo(a.z); v1[1] += bfhi(a.z); v1[2] += bflo(a.w); v1[3] += bfhi(a.w); }
;         *(u32x4*)(E.S + off) = pack8(v0, v1);
;     } else {
;         const u32x4 zw = *(const u32x4*)(E.ZB + off);
;         f32x4 x0 = {bflo(zw.x), bfhi(zw.x), bflo(zw.y), bfhi(zw.y)}, x1 = {bflo(zw.z), bfhi(zw.z), bflo(zw.w), bfhi(zw.w)};
;         if (E.pst) {
;             const f32x4* sp = (const f32x4*)(E.pst + (size_t)row * 32); float s = 0.f, q = 0.f;
; #pragma unroll
;             for (int i = 0; i < 8; ++i) { const f32x4 t = sp[i]; s += t[0] + t[2]; q += t[1] + t[3]; }
;             const float mu = s * (1.f / D), rstd = __builtin_amdgcn_rsqf(fmaxf(q * (1.f / D) - mu * mu, 0.f) + LN_EPS);
;             const f32x4 g0 = *(const f32x4*)(E.pg + col), g1 = *(const f32x4*)(E.pg + col + 4), b0 = *(const f32x4*)(E.pb + col), b1 = *(const f32x4*)(E.pb + col + 4);
;             x0 = (x0 - mu) * rstd * g0 + b0; x1 = (x1 - mu) * rstd * g1 + b1;
.Lte5_nostats:
	v_or_b32_e32 v77, s0, v179
	v_lshlrev_b64 v[0:1], 11, v[2:3]
	v_lshl_add_u64 v[0:1], s[20:21], 0, v[0:1]
	v_lshlrev_b32_e32 v80, 1, v77
	s_waitcnt lgkmcnt(0)
	s_barrier
	v_lshl_add_u64 v[0:1], v[0:1], 0, v[80:81]
	s_waitcnt vmcnt(0)
	v_mov_b32_e32 v72, v116
	v_mov_b32_e32 v73, v117
	v_mov_b32_e32 v74, v118
	v_mov_b32_e32 v75, v119
	v_add_u32_e32 v4, 0x4100, v180
	v_add_u32_e32 v5, 0x8200, v180
	v_add_u32_e32 v6, 0xc300, v180
	v_add_u32_e32 v7, 0x4108, v180
	ds_read2_b32 v[12:13], v4 offset1:1
	ds_read2_b32 v[8:9], v5 offset1:1
	ds_read2_b32 v[10:11], v6 offset1:1
	ds_read2_b32 v[18:19], v7 offset1:1
	v_add_u32_e32 v4, 0x8208, v180
	v_add_u32_e32 v5, 0xc308, v180
	v_add_u32_e32 v6, 0x4110, v180
	v_add_u32_e32 v14, 0x8210, v180
	v_add_u32_e32 v16, 0xc310, v180
	v_add_u32_e32 v22, 0x4118, v180
	v_add_u32_e32 v23, 0x8218, v180
	v_add_u32_e32 v24, 0xc318, v180
	ds_read2_b32 v[34:35], v4 offset1:1
	ds_read2_b32 v[26:27], v5 offset1:1
	ds_read2_b32 v[6:7], v6 offset1:1
	ds_read2_b32 v[4:5], v14 offset1:1
	ds_read2_b32 v[50:51], v180 offset1:1
	ds_read2_b32 v[54:55], v180 offset0:2 offset1:3
	ds_read2_b32 v[14:15], v180 offset0:4 offset1:5
	ds_read2_b32 v[20:21], v180 offset0:6 offset1:7
	ds_read2_b32 v[16:17], v16 offset1:1
	ds_read2_b32 v[28:29], v22 offset1:1
	ds_read2_b32 v[30:31], v23 offset1:1
	ds_read2_b32 v[22:23], v24 offset1:1
	ds_read2_b32 v[56:57], v182 offset1:1
	ds_read2_b32 v[58:59], v183 offset1:1
	ds_read2_b32 v[24:25], v184 offset1:1
	ds_read2_b32 v[32:33], v185 offset1:1
	ds_read2_b32 v[60:61], v190 offset1:1
	ds_read2_b32 v[62:63], v191 offset1:1
	ds_read2_b32 v[36:37], v192 offset1:1
	ds_read2_b32 v[38:39], v193 offset1:1
	ds_read2_b32 v[64:65], v194 offset1:1
	ds_read2_b32 v[66:67], v195 offset1:1
	ds_read2_b32 v[40:41], v196 offset1:1
	ds_read2_b32 v[42:43], v197 offset1:1
	ds_read2_b32 v[68:69], v198 offset1:1
	ds_read2_b32 v[70:71], v199 offset1:1
	ds_read2_b32 v[44:45], v200 offset1:1
	ds_read2_b32 v[46:47], v201 offset1:1
	s_and_b64 vcc, exec, s[2:3]
	v_lshlrev_b64 v[2:3], 7, v[2:3]
	s_waitcnt vmcnt(0)
	v_lshlrev_b32_e32 v48, 16, v72
	v_and_b32_e32 v49, 0xffff0000, v72
	v_lshlrev_b32_e32 v52, 16, v73
	v_and_b32_e32 v53, 0xffff0000, v73
	v_lshlrev_b32_e32 v72, 16, v74
	v_and_b32_e32 v73, 0xffff0000, v74
	v_lshlrev_b32_e32 v74, 16, v75
	v_and_b32_e32 v75, 0xffff0000, v75
	s_cbranch_vccz .LBB0_1530
	v_lshl_add_u64 v[78:79], s[46:47], 0, v[2:3]
	v_mov_b32_e32 v82, v120
	v_mov_b32_e32 v83, v121
	v_mov_b32_e32 v84, v122
	v_mov_b32_e32 v85, v123
	v_mov_b32_e32 v86, v124
	v_mov_b32_e32 v87, v125
	v_mov_b32_e32 v88, v126
	v_mov_b32_e32 v89, v127
	v_mov_b32_e32 v90, v128
	v_mov_b32_e32 v91, v129
	v_mov_b32_e32 v92, v130
	v_mov_b32_e32 v93, v131
	v_mov_b32_e32 v94, v132
	v_mov_b32_e32 v95, v133
	v_mov_b32_e32 v96, v134
	v_mov_b32_e32 v97, v135
	v_mov_b32_e32 v98, v136
	v_mov_b32_e32 v99, v137
	v_mov_b32_e32 v100, v138
	v_mov_b32_e32 v101, v139
	v_mov_b32_e32 v102, v140
	v_mov_b32_e32 v103, v141
	v_mov_b32_e32 v104, v142
	v_mov_b32_e32 v105, v143
	v_mov_b32_e32 v106, v144
	v_mov_b32_e32 v107, v145
	v_mov_b32_e32 v108, v146
	v_mov_b32_e32 v109, v147
	v_mov_b32_e32 v110, v148
	v_mov_b32_e32 v111, v149
	v_mov_b32_e32 v112, v150
	v_mov_b32_e32 v113, v151
	v_lshlrev_b32_e32 v77, 2, v77
	s_mov_b32 s0, 0x3a800000
	s_waitcnt vmcnt(7)
	v_pk_add_f32 v[82:83], v[82:83], v[84:85]
	s_waitcnt vmcnt(6)
	v_pk_add_f32 v[86:87], v[86:87], v[88:89]
	s_waitcnt vmcnt(5)
	v_pk_add_f32 v[90:91], v[90:91], v[92:93]
	s_waitcnt vmcnt(4)
	v_pk_add_f32 v[78:79], v[94:95], v[96:97]
	s_nop 0
	v_pk_add_f32 v[78:79], v[78:79], 0 op_sel_hi:[1,0]
	s_nop 0
	v_pk_add_f32 v[78:79], v[78:79], v[90:91]
	s_nop 0
	v_pk_add_f32 v[78:79], v[78:79], v[86:87]
	s_nop 0
	v_pk_add_f32 v[78:79], v[78:79], v[82:83]
	s_waitcnt vmcnt(0)
	v_pk_add_f32 v[82:83], v[110:111], v[112:113]
	s_nop 0
	v_pk_add_f32 v[78:79], v[78:79], v[82:83]
	v_pk_add_f32 v[82:83], v[106:107], v[108:109]
	s_nop 0
	v_pk_add_f32 v[78:79], v[78:79], v[82:83]
	v_pk_add_f32 v[82:83], v[102:103], v[104:105]
	s_nop 0
	v_pk_add_f32 v[78:79], v[78:79], v[82:83]
	v_pk_add_f32 v[82:83], v[98:99], v[100:101]
	s_nop 0
	v_pk_add_f32 v[78:79], v[78:79], v[82:83]
	v_mov_b32_e32 v82, v152
	v_mov_b32_e32 v83, v153
	v_mov_b32_e32 v84, v154
	v_mov_b32_e32 v85, v155
	v_mov_b32_e32 v86, v156
	v_mov_b32_e32 v87, v157
	v_mov_b32_e32 v88, v158
	v_mov_b32_e32 v89, v159
	v_mov_b32_e32 v90, v160
	v_mov_b32_e32 v91, v161
	v_mov_b32_e32 v92, v162
	v_mov_b32_e32 v93, v163
	v_mov_b32_e32 v94, v168
	v_mov_b32_e32 v95, v169
	v_mov_b32_e32 v96, v170
	v_mov_b32_e32 v97, v171
	v_pk_mul_f32 v[78:79], v[78:79], s[0:1] op_sel_hi:[1,0]
	s_nop 0
	v_fma_f32 v76, -v78, v78, v79
	v_max_f32_e32 v76, 0, v76
	v_add_f32_e32 v76, 0x3727c5ac, v76
	v_rsq_f32_e32 v76, v76
	v_sub_f32_e32 v53, v53, v78
	v_sub_f32_e32 v52, v52, v78
	v_sub_f32_e32 v49, v49, v78
	v_sub_f32_e32 v48, v48, v78
	v_sub_f32_e32 v75, v75, v78
	v_sub_f32_e32 v74, v74, v78
	v_sub_f32_e32 v73, v73, v78
	v_sub_f32_e32 v72, v72, v78
	v_pk_mul_f32 v[48:49], v[48:49], v[76:77] op_sel_hi:[1,0]
	v_pk_mul_f32 v[52:53], v[52:53], v[76:77] op_sel_hi:[1,0]
	v_pk_mul_f32 v[72:73], v[72:73], v[76:77] op_sel_hi:[1,0]
	v_pk_mul_f32 v[74:75], v[74:75], v[76:77] op_sel_hi:[1,0]
	s_waitcnt vmcnt(1)
	v_pk_fma_f32 v[72:73], v[82:83], v[72:73], v[90:91]
	s_waitcnt vmcnt(0)
	v_pk_fma_f32 v[52:53], v[88:89], v[52:53], v[96:97]
	v_pk_fma_f32 v[48:49], v[86:87], v[48:49], v[94:95]
	v_pk_fma_f32 v[74:75], v[84:85], v[74:75], v[92:93]

; #define LAS __attribute__((address_space(3)))
; #define BAR_LDS() do { asm volatile("s_waitcnt lgkmcnt(0)" ::: "memory"); __builtin_amdgcn_s_barrier(); asm volatile("" ::: "memory"); } while (0)
; template <int EPI> __device__ __forceinline__ void tail_gemm(LAS unsigned char* lds, const bf16* Am, const bf16* Bt, int K, const TailEpi& E, int tid_in) {
;     ...
;     LAS float* part = (LAS float*)lds + (size_t)w * 64 * 65;
; #pragma unroll
;     for (int i = 0; i < 4; ++i)
; #pragma unroll
;         for (int j = 0; j < 4; ++j)
; #pragma unroll
;             for (int r = 0; r < 4; ++r) part[(16 * i + 4 * q4 + r) * 65 + 16 * j + l15] = acc[i][j][r];
;     BAR_LDS();
;     const int rl = tid >> 3, c8 = (tid & 7) * 8, row = row0 + rl, col = col0 + c8;
;     f32x4 v0 = {0.f, 0.f, 0.f, 0.f}, v1 = v0;
; #pragma unroll
;     for (int ww = 0; ww < 8; ++ww) { const LAS float* p = (const LAS float*)lds + (size_t)ww * 64 * 65 + rl * 65 + c8;
;         v0[0] += p[0]; v0[1] += p[1]; v0[2] += p[2]; v0[3] += p[3]; v1[0] += p[4]; v1[1] += p[5]; v1[2] += p[6]; v1[3] += p[7]; }
.LBB0_1761:
	s_or_b64 exec, exec, s[2:3]
	v_add_u32_e32 v76, s1, v178
	v_ashrrev_i32_e32 v77, 31, v76
	v_or_b32_e32 v84, s0, v179
	v_lshlrev_b64 v[78:79], 10, v[76:77]
	v_or_b32_e32 v78, v78, v84
	v_lshl_add_u64 v[78:79], v[78:79], 1, s[20:21]
	global_load_dwordx4 v[68:71], v[78:79], off
	v_lshlrev_b64 v[76:77], 7, v[76:77]
	v_lshl_add_u64 v[76:77], s[44:45], 0, v[76:77]
	v_lshlrev_b32_e32 v84, 2, v84
	global_load_dwordx4 v[92:95], v[76:77], off offset:48
	global_load_dwordx4 v[96:99], v[76:77], off offset:32
	global_load_dwordx4 v[100:103], v[76:77], off offset:16
	global_load_dwordx4 v[104:107], v[76:77], off
	global_load_dwordx4 v[108:111], v[76:77], off offset:112
	global_load_dwordx4 v[112:115], v[76:77], off offset:96
	global_load_dwordx4 v[116:119], v[76:77], off offset:80
	global_load_dwordx4 v[156:159], v[76:77], off offset:64
	global_load_dwordx4 v[160:163], v84, s[48:49] offset:16
	global_load_dwordx4 v[168:171], v84, s[48:49]
	global_load_dwordx4 v[172:175], v84, s[50:51] offset:16
	global_load_dwordx4 v[72:75], v84, s[50:51]
	ds_write2_b32 v181, v60, v56 offset1:16
	ds_write2_b32 v181, v61, v57 offset0:65 offset1:81
	ds_write2_b32 v181, v62, v58 offset0:130 offset1:146
	ds_write2_b32 v181, v63, v59 offset0:195 offset1:211
	ds_write2_b32 v181, v44, v40 offset0:32 offset1:48
	ds_write2_b32 v181, v45, v41 offset0:97 offset1:113
	ds_write2_b32 v181, v46, v42 offset0:162 offset1:178
	ds_write2_b32 v181, v47, v43 offset0:227 offset1:243
	v_add_u32_e32 v40, 0x1000, v181
	ds_write2_b32 v40, v28, v24 offset0:16 offset1:32
	ds_write2_b32 v40, v29, v25 offset0:81 offset1:97
	ds_write2_b32 v40, v30, v26 offset0:146 offset1:162
	ds_write2_b32 v40, v31, v27 offset0:211 offset1:227
	ds_write2_b32 v40, v12, v8 offset0:48 offset1:64
	ds_write2_b32 v40, v13, v9 offset0:113 offset1:129
	ds_write2_b32 v40, v14, v10 offset0:178 offset1:194
	v_add_u32_e32 v8, 0x1200, v181
	ds_write2_b32 v8, v15, v11 offset0:115 offset1:131
	v_add_u32_e32 v8, 0x2000, v181
	ds_write2_b32 v8, v48, v52 offset0:32 offset1:48
	ds_write2_b32 v8, v49, v53 offset0:97 offset1:113
	ds_write2_b32 v8, v50, v54 offset0:162 offset1:178
	ds_write2_b32 v8, v51, v55 offset0:227 offset1:243
	ds_write2_b32 v8, v32, v36 offset0:64 offset1:80
	ds_write2_b32 v8, v33, v37 offset0:129 offset1:145
	ds_write2_b32 v8, v34, v38 offset0:194 offset1:210
	v_add_u32_e32 v8, 0x2400, v181
	ds_write2_b32 v8, v35, v39 offset0:3 offset1:19
	v_add_u32_e32 v8, 0x3000, v181
	v_add_u32_e32 v9, 0x3200, v181
	ds_write2_b32 v8, v16, v20 offset0:48 offset1:64
	ds_write2_b32 v8, v17, v21 offset0:113 offset1:129
	ds_write2_b32 v8, v18, v22 offset0:178 offset1:194
	ds_write2_b32 v9, v19, v23 offset0:115 offset1:131
	ds_write2_b32 v8, v0, v4 offset0:80 offset1:96
	ds_write2_b32 v8, v1, v5 offset0:145 offset1:161
	ds_write2_b32 v8, v2, v6 offset0:210 offset1:226
	v_add_u32_e32 v0, 0x3400, v181
	ds_write2_b32 v0, v3, v7 offset0:19 offset1:35
	s_waitcnt lgkmcnt(0)
	s_barrier
	v_add_u32_e32 v1, 0x4100, v180
	ds_read2_b32 v[2:3], v180 offset1:1
	ds_read2_b32 v[4:5], v1 offset1:1
	v_add_u32_e32 v1, 0x8200, v180
	ds_read2_b32 v[6:7], v1 offset1:1
	v_add_u32_e32 v1, 0xc300, v180
	ds_read2_b32 v[8:9], v1 offset1:1
	ds_read2_b32 v[10:11], v182 offset1:1
	ds_read2_b32 v[12:13], v190 offset1:1
	ds_read2_b32 v[14:15], v194 offset1:1
	ds_read2_b32 v[16:17], v198 offset1:1
	ds_read2_b32 v[18:19], v180 offset0:2 offset1:3
	v_add_u32_e32 v1, 0x4108, v180
	ds_read2_b32 v[20:21], v1 offset1:1
	v_add_u32_e32 v1, 0x8208, v180
	ds_read2_b32 v[22:23], v1 offset1:1
	s_waitcnt lgkmcnt(2)
	v_pk_add_f32 v[18:19], v[18:19], 0 op_sel_hi:[1,0]
	v_pk_add_f32 v[2:3], v[2:3], 0 op_sel_hi:[1,0]
	v_add_u32_e32 v1, 0xc308, v180
	v_pk_add_f32 v[2:3], v[2:3], v[4:5]
	s_waitcnt lgkmcnt(1)
	v_pk_add_f32 v[4:5], v[18:19], v[20:21]
	ds_read2_b32 v[24:25], v1 offset1:1
	ds_read2_b32 v[26:27], v183 offset1:1
	ds_read2_b32 v[28:29], v191 offset1:1
	ds_read2_b32 v[30:31], v195 offset1:1
	ds_read2_b32 v[32:33], v199 offset1:1
	s_waitcnt lgkmcnt(5)
	v_pk_add_f32 v[4:5], v[4:5], v[22:23]
	v_pk_add_f32 v[2:3], v[2:3], v[6:7]
	s_waitcnt lgkmcnt(4)
	v_pk_add_f32 v[4:5], v[4:5], v[24:25]
	v_pk_add_f32 v[2:3], v[2:3], v[8:9]
	s_waitcnt lgkmcnt(3)
	v_pk_add_f32 v[4:5], v[4:5], v[26:27]
	v_pk_add_f32 v[2:3], v[2:3], v[10:11]
	s_waitcnt lgkmcnt(2)
	v_pk_add_f32 v[4:5], v[4:5], v[28:29]
	v_pk_add_f32 v[2:3], v[2:3], v[12:13]
	s_waitcnt lgkmcnt(1)
	v_pk_add_f32 v[4:5], v[4:5], v[30:31]
	v_pk_add_f32 v[2:3], v[2:3], v[14:15]
	v_add_u32_e32 v1, 0x4110, v180
	v_pk_add_f32 v[16:17], v[2:3], v[16:17]
	s_waitcnt lgkmcnt(0)
	v_pk_add_f32 v[18:19], v[4:5], v[32:33]
	ds_read2_b32 v[2:3], v180 offset0:4 offset1:5
	ds_read2_b32 v[4:5], v1 offset1:1
	v_add_u32_e32 v1, 0x8210, v180
	ds_read2_b32 v[6:7], v1 offset1:1
	v_add_u32_e32 v1, 0xc310, v180
	ds_read2_b32 v[8:9], v1 offset1:1
	ds_read2_b32 v[10:11], v184 offset1:1
	ds_read2_b32 v[12:13], v192 offset1:1
	ds_read2_b32 v[14:15], v196 offset1:1
	ds_read2_b32 v[20:21], v200 offset1:1
	ds_read2_b32 v[22:23], v180 offset0:6 offset1:7
	v_add_u32_e32 v1, 0x4118, v180
	ds_read2_b32 v[24:25], v1 offset1:1
	v_add_u32_e32 v1, 0x8218, v180
	ds_read2_b32 v[26:27], v1 offset1:1
	s_waitcnt lgkmcnt(2)
; #define LAS __attribute__((address_space(3)))
; __device__ __forceinline__ float bflo(unsigned w) { return __uint_as_float(w << 16); }
; __device__ __forceinline__ float bfhi(unsigned w) { return __uint_as_float(w & 0xffff0000u); }
; template <int EPI> __device__ __forceinline__ void tail_gemm(LAS unsigned char* lds, const bf16* Am, const bf16* Bt, int K, const TailEpi& E, int tid_in) {
;     ...
;     for (int ww = 0; ww < 8; ++ww) { const LAS float* p = (const LAS float*)lds + (size_t)ww * 64 * 65 + rl * 65 + c8;
;         v0[0] += p[0]; v0[1] += p[1]; v0[2] += p[2]; v0[3] += p[3]; v1[0] += p[4]; v1[1] += p[5]; v1[2] += p[6]; v1[3] += p[7]; }
;     const size_t off = (size_t)row * 1024 + col;
;     if (EPI == 0 || EPI == 1) {
;         const u32x4 s = *(const u32x4*)(E.S + off);
;         v0[0] *= bflo(s.x); v0[1] *= bfhi(s.x); v0[2] *= bflo(s.y); v0[3] *= bfhi(s.y); v1[0] *= bflo(s.z); v1[1] *= bfhi(s.z); v1[2] *= bflo(s.w); v1[3] *= bfhi(s.w);
;         if (EPI == 1) { const u32x4 a = *(const u32x4*)(E.A + off);
;             v0[0] += bflo(a.x); v0[1] += bfhi(a.x); v0[2] += bflo(a.y); v0[3] += bfhi(a.y); v1[0] += bflo(a.z); v1[1] += bfhi(a.z); v1[2] += bflo(a.w); v1[3] += bfhi(a.w); }
;         *(u32x4*)(E.S + off) = pack8(v0, v1);
;     } else {
;         const u32x4 zw = *(const u32x4*)(E.ZB + off);
;         f32x4 x0 = {bflo(zw.x), bfhi(zw.x), bflo(zw.y), bfhi(zw.y)}, x1 = {bflo(zw.z), bfhi(zw.z), bflo(zw.w), bfhi(zw.w)};
;         if (E.pst) {
;             const f32x4* sp = (const f32x4*)(E.pst + (size_t)row * 32); float s = 0.f, q = 0.f;
; #pragma unroll
;             for (int i = 0; i < 8; ++i) { const f32x4 t = sp[i]; s += t[0] + t[2]; q += t[1] + t[3]; }
;             const float mu = s * (1.f / D), rstd = __builtin_amdgcn_rsqf(fmaxf(q * (1.f / D) - mu * mu, 0.f) + LN_EPS);
;             const f32x4 g0 = *(const f32x4*)(E.pg + col), g1 = *(const f32x4*)(E.pg + col + 4), b0 = *(const f32x4*)(E.pb + col), b1 = *(const f32x4*)(E.pb + col + 4);
;             x0 = (x0 - mu) * rstd * g0 + b0; x1 = (x1 - mu) * rstd * g1 + b1;
;         }
;         x0 = x0 * ALPHA + v0; x1 = x1 * ALPHA + v1;
;         if (E.Z) { *(f32x4*)(E.Z + off) = x0; *(f32x4*)(E.Z + off + 4) = x1; }
;         *(u32x4*)(E.ZB + off) = pack8(x0, x1);
	v_pk_add_f32 v[22:23], v[22:23], 0 op_sel_hi:[1,0]
	v_pk_add_f32 v[2:3], v[2:3], 0 op_sel_hi:[1,0]
	v_add_u32_e32 v1, 0xc318, v180
	v_pk_add_f32 v[2:3], v[2:3], v[4:5]
	s_waitcnt lgkmcnt(1)
	v_pk_add_f32 v[4:5], v[22:23], v[24:25]
	v_add_u32_e32 v0, s1, v178
	ds_read2_b32 v[28:29], v1 offset1:1
	ds_read2_b32 v[30:31], v185 offset1:1
	ds_read2_b32 v[32:33], v193 offset1:1
	ds_read2_b32 v[34:35], v197 offset1:1
	ds_read2_b32 v[36:37], v201 offset1:1
	s_waitcnt lgkmcnt(5)
	v_pk_add_f32 v[4:5], v[4:5], v[26:27]
	v_pk_add_f32 v[2:3], v[2:3], v[6:7]
	s_waitcnt lgkmcnt(4)
	v_pk_add_f32 v[4:5], v[4:5], v[28:29]
	v_pk_add_f32 v[2:3], v[2:3], v[8:9]
	v_ashrrev_i32_e32 v1, 31, v0
	s_waitcnt lgkmcnt(3)
	v_pk_add_f32 v[4:5], v[4:5], v[30:31]
	v_pk_add_f32 v[2:3], v[2:3], v[10:11]
	v_or_b32_e32 v41, s0, v179
	v_lshlrev_b64 v[28:29], 10, v[0:1]
	v_pk_add_f32 v[2:3], v[2:3], v[12:13]
	s_waitcnt lgkmcnt(2)
	v_pk_add_f32 v[4:5], v[4:5], v[32:33]
	v_or_b32_e32 v28, v28, v41
	s_waitcnt lgkmcnt(1)
	v_pk_add_f32 v[4:5], v[4:5], v[34:35]
	v_pk_add_f32 v[2:3], v[2:3], v[14:15]
	v_lshl_add_u64 v[26:27], v[28:29], 1, s[20:21]
	v_pk_add_f32 v[20:21], v[2:3], v[20:21]
	s_waitcnt lgkmcnt(0)
	v_pk_add_f32 v[22:23], v[4:5], v[36:37]
	s_waitcnt vmcnt(0)
	v_mov_b32_e32 v2, v68
	v_mov_b32_e32 v3, v69
	v_mov_b32_e32 v4, v70
	v_mov_b32_e32 v5, v71
	v_lshlrev_b64 v[24:25], 7, v[0:1]
	v_lshl_add_u64 v[32:33], s[44:45], 0, v[24:25]
	s_mov_b32 s0, 0x3a800000
	s_and_b64 vcc, exec, s[46:47]
	s_waitcnt vmcnt(0)
	v_lshlrev_b32_e32 v37, 16, v2
	v_and_b32_e32 v39, 0xffff0000, v2
	v_lshlrev_b32_e32 v38, 16, v3
	v_and_b32_e32 v40, 0xffff0000, v3
	v_lshlrev_b32_e32 v31, 16, v4
	v_and_b32_e32 v35, 0xffff0000, v4
	v_lshlrev_b32_e32 v34, 16, v5
	v_and_b32_e32 v36, 0xffff0000, v5
	v_mov_b32_e32 v0, v92
	v_mov_b32_e32 v1, v93
	v_mov_b32_e32 v2, v94
	v_mov_b32_e32 v3, v95
	v_mov_b32_e32 v4, v96
	v_mov_b32_e32 v5, v97
	v_mov_b32_e32 v6, v98
	v_mov_b32_e32 v7, v99
	v_mov_b32_e32 v8, v100
	v_mov_b32_e32 v9, v101
	v_mov_b32_e32 v10, v102
	v_mov_b32_e32 v11, v103
	v_mov_b32_e32 v12, v104
	v_mov_b32_e32 v13, v105
	v_mov_b32_e32 v14, v106
	v_mov_b32_e32 v15, v107
	v_mov_b32_e32 v42, v108
	v_mov_b32_e32 v43, v109
	v_mov_b32_e32 v44, v110
	v_mov_b32_e32 v45, v111
	v_mov_b32_e32 v46, v112
	v_mov_b32_e32 v47, v113
	v_mov_b32_e32 v48, v114
	v_mov_b32_e32 v49, v115
	v_mov_b32_e32 v50, v116
	v_mov_b32_e32 v51, v117
	v_mov_b32_e32 v52, v118
	v_mov_b32_e32 v53, v119
	v_mov_b32_e32 v54, v156
	v_mov_b32_e32 v55, v157
	v_mov_b32_e32 v56, v158
	v_mov_b32_e32 v57, v159
	s_waitcnt vmcnt(7)
	v_pk_add_f32 v[0:1], v[0:1], v[2:3]
	s_waitcnt vmcnt(6)
	v_pk_add_f32 v[4:5], v[4:5], v[6:7]
	s_waitcnt vmcnt(5)
	v_pk_add_f32 v[8:9], v[8:9], v[10:11]
	s_waitcnt vmcnt(4)
	v_pk_add_f32 v[12:13], v[12:13], v[14:15]
	s_waitcnt vmcnt(0)
	v_pk_add_f32 v[2:3], v[54:55], v[56:57]
	v_pk_add_f32 v[12:13], v[12:13], 0 op_sel_hi:[1,0]
	s_nop 0
	v_pk_add_f32 v[8:9], v[12:13], v[8:9]
	v_lshlrev_b32_e32 v12, 2, v41
	v_pk_add_f32 v[4:5], v[8:9], v[4:5]
	s_nop 0
	v_pk_add_f32 v[0:1], v[4:5], v[0:1]
	s_nop 0
	v_pk_add_f32 v[0:1], v[0:1], v[2:3]
	v_pk_add_f32 v[2:3], v[50:51], v[52:53]
	s_nop 0
	v_pk_add_f32 v[0:1], v[0:1], v[2:3]
	v_pk_add_f32 v[2:3], v[46:47], v[48:49]
	s_nop 0
	v_pk_add_f32 v[0:1], v[0:1], v[2:3]
	v_pk_add_f32 v[2:3], v[42:43], v[44:45]
	s_nop 0
	v_pk_add_f32 v[0:1], v[0:1], v[2:3]
	s_nop 0
	v_pk_mul_f32 v[32:33], v[0:1], s[0:1] op_sel_hi:[1,0]
	s_nop 0
	v_fma_f32 v0, -v32, v32, v33
	v_max_f32_e32 v0, 0, v0
	v_add_f32_e32 v0, 0x3727c5ac, v0
	v_rsq_f32_e32 v30, v0
	v_mov_b32_e32 v0, v160
	v_mov_b32_e32 v1, v161
	v_mov_b32_e32 v2, v162
	v_mov_b32_e32 v3, v163
	v_mov_b32_e32 v8, v168
	v_mov_b32_e32 v9, v169
	v_mov_b32_e32 v10, v170
	v_mov_b32_e32 v11, v171
	v_mov_b32_e32 v4, v172
	v_mov_b32_e32 v5, v173
	v_mov_b32_e32 v6, v174
	v_mov_b32_e32 v7, v175
	s_nop 0
	v_mov_b32_e32 v12, v72
	v_mov_b32_e32 v13, v73
	v_mov_b32_e32 v14, v74
	v_mov_b32_e32 v15, v75
	v_sub_f32_e32 v43, v39, v32
	v_sub_f32_e32 v42, v37, v32
	v_sub_f32_e32 v39, v40, v32
	v_sub_f32_e32 v38, v38, v32
	v_pk_mul_f32 v[38:39], v[38:39], v[30:31] op_sel_hi:[1,0]
	v_pk_mul_f32 v[40:41], v[42:43], v[30:31] op_sel_hi:[1,0]
	s_waitcnt vmcnt(0)
	v_pk_fma_f32 v[10:11], v[10:11], v[38:39], v[14:15]
	v_pk_fma_f32 v[8:9], v[8:9], v[40:41], v[12:13]
	v_sub_f32_e32 v13, v35, v32
	v_sub_f32_e32 v12, v31, v32
	v_sub_f32_e32 v15, v36, v32
	v_sub_f32_e32 v14, v34, v32
	v_pk_mul_f32 v[14:15], v[14:15], v[30:31] op_sel_hi:[1,0]
	v_pk_mul_f32 v[12:13], v[12:13], v[30:31] op_sel_hi:[1,0]
	v_pk_fma_f32 v[2:3], v[2:3], v[14:15], v[6:7]
	v_pk_fma_f32 v[0:1], v[0:1], v[12:13], v[4:5]
	v_pk_fma_f32 v[6:7], v[10:11], s[34:35], v[18:19] op_sel_hi:[1,0,1]
	v_pk_fma_f32 v[4:5], v[8:9], s[34:35], v[16:17] op_sel_hi:[1,0,1]
	v_pk_fma_f32 v[2:3], v[2:3], s[34:35], v[22:23] op_sel_hi:[1,0,1]
	v_pk_fma_f32 v[0:1], v[0:1], s[34:35], v[20:21] op_sel_hi:[1,0,1]
	s_cbranch_vccz .LBB0_1763
	v_lshl_add_u64 v[8:9], v[28:29], 2, s[96:97]
	global_store_dwordx4 v[8:9], v[4:7], off
	global_store_dwordx4 v[8:9], v[0:3], off offset:16
